# stack + NSA sliding-window loop on LDS-DMA with two private LDS buffers in the dead importance-slot region, one barrier per step
# speedup vs baseline: 1.0042x; 1.0042x over previous
; DI float bflo(unsigned u) { return __uint_as_float(u << 16); }
; DI float bfhi(unsigned u) { return __uint_as_float(u & 0xffff0000u); }
; template <bool FIRST>
; DI void nsa_flush(const int quad, bf16_t* optr, const AttnSt& st, const float (&sc)[2]) {
; #pragma unroll
;   for (int h = 0; h < 2; ++h)
; #pragma unroll
;     for (int dt = 0; dt < 4; ++dt) {
;       uint2* q = (uint2*)(optr + h * 64 + dt * 16 + quad * 4);
;       f32x4 o = st.O[h][dt] * sc[h];
;       if (!FIRST) {
;         uint2 pv = *q;
;         o[0] += bflo(pv.x); o[1] += bfhi(pv.x); o[2] += bflo(pv.y); o[3] += bfhi(pv.y);
;       }
;       uint2 u;
;       u.x = pack2(o[0], o[1]);
;       u.y = pack2(o[2], o[3]);
;       *q = u;
;     }
; }
; template <bool FX>
; DI void nsa_tile(const Params& p, int b, int g, int tile, bf16_t* lds, const float CL) {
;     ...
;     st_reset(st);
;     {
;       const bf16_t* kb = zb + C_KW + g * 64;
;       const int s0 = (cur >= 8) ? cur - 8 : 0;
;       tile64_gload(tid, rk0, rk1, kb + (size_t)s0 * 64 * ZS, ZS);
;       tile64_gload(tid, rv0, rv1, vwT + s0 * 64, TS);
.LBB0_679:
	s_or_b64 exec, exec, s[2:3]
	s_lshl_b32 s28, s7, 1
	v_lshl_add_u64 v[158:159], v[128:129], 0, s[28:29]
	global_load_dwordx2 v[46:47], v[158:159], off
	v_mov_b32_e32 v49, v48
	v_mov_b32_e32 v178, v186
	s_mov_b32 s71, s26
	s_mov_b32 s28, s27
	s_waitcnt vmcnt(0)
	v_lshlrev_b32_e32 v54, 16, v46
	v_and_b32_e32 v55, 0xffff0000, v46
	v_lshlrev_b32_e32 v46, 16, v47
	v_and_b32_e32 v47, 0xffff0000, v47
	v_pk_fma_f32 v[50:51], v[50:51], v[56:57], v[54:55]
	v_pk_fma_f32 v[46:47], v[52:53], v[58:59], v[46:47]
	v_cvt_pk_bf16_f32 v50, v50, v51
	v_cvt_pk_bf16_f32 v51, v46, v47
	global_load_dwordx2 v[46:47], v[158:159], off offset:32
	s_nop 0
	global_store_dwordx2 v[158:159], v[50:51], off
	s_waitcnt vmcnt(1)
	v_lshlrev_b32_e32 v50, 16, v46
	v_and_b32_e32 v51, 0xffff0000, v46
	v_lshlrev_b32_e32 v46, 16, v47
	v_and_b32_e32 v47, 0xffff0000, v47
	v_pk_fma_f32 v[42:43], v[42:43], v[56:57], v[50:51]
	v_pk_fma_f32 v[44:45], v[44:45], v[58:59], v[46:47]
	v_cvt_pk_bf16_f32 v42, v42, v43
	v_cvt_pk_bf16_f32 v43, v44, v45
	global_store_dwordx2 v[158:159], v[42:43], off offset:32
	global_load_dwordx2 v[42:43], v[158:159], off offset:64
	v_mov_b32_e32 v46, 0
	v_mov_b32_e32 v47, v46
	v_mov_b32_e32 v54, v46
	v_mov_b32_e32 v55, v46
	v_mov_b32_e32 v50, v46
	v_mov_b32_e32 v51, v46
	v_mov_b32_e32 v52, v46
	v_mov_b32_e32 v53, v46
	s_waitcnt vmcnt(0)
	v_lshlrev_b32_e32 v44, 16, v42
	v_and_b32_e32 v45, 0xffff0000, v42
	v_lshlrev_b32_e32 v42, 16, v43
	v_and_b32_e32 v43, 0xffff0000, v43
	v_pk_fma_f32 v[38:39], v[38:39], v[56:57], v[44:45]
	v_pk_fma_f32 v[40:41], v[40:41], v[58:59], v[42:43]
	v_cvt_pk_bf16_f32 v38, v38, v39
	v_cvt_pk_bf16_f32 v39, v40, v41
	global_store_dwordx2 v[158:159], v[38:39], off offset:64
	global_load_dwordx2 v[38:39], v[158:159], off offset:96
	v_mov_b32_e32 v42, v46
	v_mov_b32_e32 v43, v46
	v_mov_b32_e32 v44, v46
	v_mov_b32_e32 v45, v46
	s_waitcnt vmcnt(0)
	v_lshlrev_b32_e32 v40, 16, v38
	v_and_b32_e32 v41, 0xffff0000, v38
	v_lshlrev_b32_e32 v38, 16, v39
	v_and_b32_e32 v39, 0xffff0000, v39
	v_pk_fma_f32 v[34:35], v[34:35], v[56:57], v[40:41]
	v_pk_fma_f32 v[36:37], v[36:37], v[58:59], v[38:39]
	v_cvt_pk_bf16_f32 v34, v34, v35
	v_cvt_pk_bf16_f32 v35, v36, v37
	global_load_dwordx2 v[36:37], v[158:159], off offset:128
	v_mov_b32_e32 v40, v46
	global_store_dwordx2 v[158:159], v[34:35], off offset:96
	v_mov_b32_e32 v34, v48
	v_mov_b32_e32 v35, v48
	v_mov_b32_e32 v41, v46
	v_mov_b32_e32 v56, v46
	v_mov_b32_e32 v57, v46
	s_waitcnt vmcnt(1)
	v_lshlrev_b32_e32 v38, 16, v36
	v_and_b32_e32 v39, 0xffff0000, v36
	v_lshlrev_b32_e32 v36, 16, v37
	v_and_b32_e32 v37, 0xffff0000, v37
	v_pk_fma_f32 v[30:31], v[30:31], v[34:35], v[38:39]
	v_pk_fma_f32 v[32:33], v[32:33], v[48:49], v[36:37]
	v_cvt_pk_bf16_f32 v30, v30, v31
	v_cvt_pk_bf16_f32 v31, v32, v33
	global_store_dwordx2 v[158:159], v[30:31], off offset:128
	global_load_dwordx2 v[30:31], v[158:159], off offset:160
	v_mov_b32_e32 v38, v46
	v_mov_b32_e32 v39, v46
	v_mov_b32_e32 v36, v46
	v_mov_b32_e32 v37, v46
	s_waitcnt vmcnt(0)
	v_lshlrev_b32_e32 v32, 16, v30
	v_and_b32_e32 v33, 0xffff0000, v30
	v_lshlrev_b32_e32 v30, 16, v31
	v_and_b32_e32 v31, 0xffff0000, v31
	v_pk_fma_f32 v[26:27], v[26:27], v[34:35], v[32:33]
	v_pk_fma_f32 v[28:29], v[28:29], v[48:49], v[30:31]
	v_cvt_pk_bf16_f32 v26, v26, v27
	v_cvt_pk_bf16_f32 v27, v28, v29
	global_store_dwordx2 v[158:159], v[26:27], off offset:160
	global_load_dwordx2 v[26:27], v[158:159], off offset:192
	v_mov_b32_e32 v30, v46
	v_mov_b32_e32 v31, v46
	v_mov_b32_e32 v32, v46
	v_mov_b32_e32 v33, v46
	s_waitcnt vmcnt(0)
	v_lshlrev_b32_e32 v28, 16, v26
	v_and_b32_e32 v29, 0xffff0000, v26
	v_lshlrev_b32_e32 v26, 16, v27
	v_and_b32_e32 v27, 0xffff0000, v27
	v_pk_fma_f32 v[22:23], v[22:23], v[34:35], v[28:29]
	v_pk_fma_f32 v[24:25], v[24:25], v[48:49], v[26:27]
	v_cvt_pk_bf16_f32 v22, v22, v23
	v_cvt_pk_bf16_f32 v23, v24, v25
	global_store_dwordx2 v[158:159], v[22:23], off offset:192
	global_load_dwordx2 v[22:23], v[158:159], off offset:224
	v_mov_b32_e32 v26, v46
	v_mov_b32_e32 v27, v46
	v_mov_b32_e32 v28, v46
	v_mov_b32_e32 v29, v46
	s_waitcnt vmcnt(0)
	v_lshlrev_b32_e32 v24, 16, v22
	v_and_b32_e32 v25, 0xffff0000, v22
	v_lshlrev_b32_e32 v22, 16, v23
	v_and_b32_e32 v23, 0xffff0000, v23
	v_pk_fma_f32 v[18:19], v[18:19], v[34:35], v[24:25]
	v_pk_fma_f32 v[20:21], v[20:21], v[48:49], v[22:23]
	v_cvt_pk_bf16_f32 v18, v18, v19
	v_cvt_pk_bf16_f32 v19, v20, v21
	global_store_dwordx2 v[158:159], v[18:19], off offset:224
	s_and_b32 s88, s76, 0xffff3fff
	s_or_b32 s88, s88, 0x4000
	s_movk_i32 s84, 0x800
	s_mov_b32 s85, 0
	v_lshl_add_u64 v[58:59], v[146:147], 0, v[218:219]
	v_lshl_add_u64 v[60:61], v[148:149], 0, v[218:219]
	v_lshl_add_u64 v[62:63], v[150:151], 0, v[218:219]
	v_lshl_add_u64 v[64:65], v[152:153], 0, v[218:219]
	v_lshl_add_u64 v[58:59], v[58:59], 0, s[84:85]
	v_lshl_add_u64 v[60:61], v[60:61], 0, s[84:85]
	s_mov_b32 m0, s88
	s_nop 0
	global_load_lds_dwordx4 v[58:59], off
	s_add_u32 m0, s88, 0x1000
	s_nop 0
	global_load_lds_dwordx4 v[60:61], off
	s_add_u32 m0, s88, 0x2000
	s_nop 0
	global_load_lds_dwordx4 v[62:63], off
	s_add_u32 m0, s88, 0x3000
	s_nop 0
	global_load_lds_dwordx4 v[64:65], off
	s_xor_b32 s88, s88, 0xc000
	v_xor_b32_e32 v188, 0x4000, v188
	v_xor_b32_e32 v189, 0x4000, v189
	v_xor_b32_e32 v190, 0x4000, v190
	v_xor_b32_e32 v191, 0x4000, v191
	v_xor_b32_e32 v207, 0x4000, v207
	v_xor_b32_e32 v208, 0x4000, v208
	v_xor_b32_e32 v209, 0x4000, v209
	v_xor_b32_e32 v210, 0x4000, v210
	v_xor_b32_e32 v211, 0x4000, v211
	v_xor_b32_e32 v212, 0x4000, v212
	v_xor_b32_e32 v213, 0x4000, v213
	v_xor_b32_e32 v214, 0x4000, v214
	s_movk_i32 s89, 0x4000
	v_mov_b32_e32 v48, v46
	v_mov_b32_e32 v49, v46
	v_mov_b32_e32 v34, v46
	v_mov_b32_e32 v35, v46
	v_mov_b32_e32 v22, v46
	v_mov_b32_e32 v23, v46
	v_mov_b32_e32 v24, v46
	v_mov_b32_e32 v25, v46
	v_mov_b32_e32 v18, v46
	v_mov_b32_e32 v19, v46
	v_mov_b32_e32 v20, v46
	v_mov_b32_e32 v21, v46
	s_branch .LBB0_681
; template <int MODE, bool FX>
; DI void attn_compute(const int lane, const bf16_t* Ks, const bf16_t* Vs, const bf16x8 (&qf)[2][2], AttnSt& st, const float (&invl)[2],
;                      int lo, int hi, float (&impA)[4], float (&impE)[4], const float CL) {
;     ...
;   if (__all(full || none)) {
;     constexpr float L2E = 1.4426950408889634f;
; #pragma unroll
;     for (int hh = 0; hh < 2; ++hh) {
;       float mL;
;       float il = 1.f;
;       if (FX) {
;         mL = full ? CL : 1e30f;
;         if (MODE == 1) il = invl[hh];
;       } else if (MODE != 1) {
;         float mx = -1e30f;
; #pragma unroll
;         for (int kt = 0; kt < 4; ++kt)
; #pragma unroll
;           for (int j = 0; j < 4; ++j) mx = fmaxf(mx, S[kt][hh][j]);
;         mx = full ? mx : -1e30f;
;         mx = fmaxf(mx, shx(mx, 16, lane));
;         mx = fmaxf(mx, shx(mx, 32, lane));
;         const float m_new = fmaxf(st.m[hh], mx);
;         const float alpha = __expf(st.m[hh] - m_new);
;         st.m[hh] = m_new;
;         st.l[hh] *= alpha;
;         if (MODE == 2) {
; #pragma unroll
;           for (int dt = 0; dt < 4; ++dt) st.O[hh][dt] *= alpha;
;         }
;         mL = full ? m_new * L2E : 1e30f;
;       } else {
;         mL = full ? st.m[hh] * L2E : 1e30f;
;         il = invl[hh];
;       }
;       float rs = 0.f;
; #pragma unroll
;       for (int kt = 0; kt < 4; ++kt) {
;         float a = 0.f;
; #pragma unroll
;         for (int j = 0; j < 4; ++j) {
;           float pv = __builtin_amdgcn_exp2f(fmaf(S[kt][hh][j], L2E, -mL));
;           if (MODE == 1) pv *= il;
;           S[kt][hh][j] = pv;
;           a += pv;
;         }
;         rs += a;
;         if (MODE == 1) {
;           impA[kt] += a;
;           impE[kt] += S[kt][hh][3];
;         }
;       }
;       if (MODE != 1 && !(FX && MODE == 2)) st.l[hh] += rs;
;       if (MODE != 0) {
; #pragma unroll
;         for (int c = 0; c < 2; ++c)
;           pf[hh][c] = mk8(pack2(S[2 * c][hh][0], S[2 * c][hh][1]), pack2(S[2 * c][hh][2], S[2 * c][hh][3]),
;                           pack2(S[2 * c + 1][hh][0], S[2 * c + 1][hh][1]), pack2(S[2 * c + 1][hh][2], S[2 * c + 1][hh][3]));
;       }
;     }
;     ...
;   if (MODE != 0) {
; #pragma unroll
;     for (int dt = 0; dt < 4; ++dt) {
;       const int row = dt * 16 + col;
;       const int sw = (row >> 1) & 7;
; #pragma unroll
;       for (int c = 0; c < 2; ++c) {
.Lwin_fast:
	ds_read_b128 v[220:223], v188
	ds_read_b128 v[224:227], v188 offset:2048
	ds_read_b128 v[228:231], v188 offset:4096
	ds_read_b128 v[232:235], v189
	ds_read_b128 v[236:239], v190
	ds_read_b128 v[240:243], v190 offset:2048
	ds_read_b128 v[244:247], v190 offset:4096
	ds_read_b128 v[198:201], v191
	s_waitcnt lgkmcnt(7)
	v_mfma_f32_16x16x32_bf16 v[98:101], v[220:223], v[2:5], 0
	s_waitcnt lgkmcnt(6)
	v_mfma_f32_16x16x32_bf16 v[106:109], v[224:227], v[2:5], 0
	s_waitcnt lgkmcnt(5)
	v_mfma_f32_16x16x32_bf16 v[102:105], v[228:231], v[2:5], 0
	s_waitcnt lgkmcnt(4)
	v_mfma_f32_16x16x32_bf16 v[110:113], v[232:235], v[2:5], 0
	s_waitcnt lgkmcnt(3)
	v_mfma_f32_16x16x32_bf16 v[98:101], v[236:239], v[6:9], v[98:101]
	s_waitcnt lgkmcnt(2)
	v_mfma_f32_16x16x32_bf16 v[106:109], v[240:243], v[6:9], v[106:109]
	s_waitcnt lgkmcnt(1)
	v_mfma_f32_16x16x32_bf16 v[102:105], v[244:247], v[6:9], v[102:105]
	s_waitcnt lgkmcnt(0)
	v_mfma_f32_16x16x32_bf16 v[110:113], v[198:201], v[6:9], v[110:113]
	v_mfma_f32_16x16x32_bf16 v[90:93], v[220:223], v[10:13], 0
	v_mfma_f32_16x16x32_bf16 v[94:97], v[224:227], v[10:13], 0
	v_mfma_f32_16x16x32_bf16 v[82:85], v[228:231], v[10:13], 0
	v_mfma_f32_16x16x32_bf16 v[86:89], v[232:235], v[10:13], 0
	v_fmamk_f32 v74, v98, 0x3fb8aa3b, v205
	v_fmamk_f32 v75, v99, 0x3fb8aa3b, v205
	v_mfma_f32_16x16x32_bf16 v[90:93], v[236:239], v[14:17], v[90:93]
	v_fmamk_f32 v76, v100, 0x3fb8aa3b, v205
	v_fmamk_f32 v77, v101, 0x3fb8aa3b, v205
	v_mfma_f32_16x16x32_bf16 v[94:97], v[240:243], v[14:17], v[94:97]
	v_fmamk_f32 v78, v106, 0x3fb8aa3b, v205
	v_fmamk_f32 v79, v107, 0x3fb8aa3b, v205
	v_mfma_f32_16x16x32_bf16 v[82:85], v[244:247], v[14:17], v[82:85]
	v_fmamk_f32 v80, v108, 0x3fb8aa3b, v205
	v_fmamk_f32 v81, v109, 0x3fb8aa3b, v205
	v_mfma_f32_16x16x32_bf16 v[86:89], v[198:201], v[14:17], v[86:89]
	ds_read_b64 v[220:221], v207 offset:8192
	v_fmamk_f32 v160, v102, 0x3fb8aa3b, v205
	ds_read_b64 v[222:223], v208 offset:8192
	v_fmamk_f32 v161, v103, 0x3fb8aa3b, v205
	ds_read_b64 v[224:225], v209 offset:8192
	v_fmamk_f32 v164, v104, 0x3fb8aa3b, v205
	ds_read_b64 v[226:227], v210 offset:8192
	v_fmamk_f32 v165, v105, 0x3fb8aa3b, v205
	ds_read_b64 v[228:229], v207 offset:10240
	v_fmamk_f32 v166, v110, 0x3fb8aa3b, v205
	ds_read_b64 v[230:231], v208 offset:10240
	v_fmamk_f32 v167, v111, 0x3fb8aa3b, v205
	ds_read_b64 v[232:233], v209 offset:10240
	v_fmamk_f32 v168, v112, 0x3fb8aa3b, v205
	ds_read_b64 v[234:235], v210 offset:10240
	v_fmamk_f32 v169, v113, 0x3fb8aa3b, v205
	ds_read_b64 v[236:237], v207 offset:12288
	v_exp_f32_e32 v74, v74
	ds_read_b64 v[238:239], v208 offset:12288
	v_exp_f32_e32 v75, v75
	ds_read_b64 v[240:241], v209 offset:12288
	v_exp_f32_e32 v76, v76
	ds_read_b64 v[242:243], v210 offset:12288
	v_exp_f32_e32 v77, v77
	ds_read_b64 v[244:245], v211 offset:8192
	v_exp_f32_e32 v78, v78
	ds_read_b64 v[246:247], v212 offset:8192
	v_exp_f32_e32 v79, v79
	ds_read_b64 v[198:199], v213 offset:8192
	v_exp_f32_e32 v80, v80
	ds_read_b64 v[200:201], v214 offset:8192
	v_exp_f32_e32 v81, v81
	v_exp_f32_e32 v160, v160
	v_exp_f32_e32 v161, v161
	v_exp_f32_e32 v164, v164
	v_exp_f32_e32 v165, v165
	v_exp_f32_e32 v166, v166
	v_exp_f32_e32 v167, v167
	v_exp_f32_e32 v168, v168
	v_exp_f32_e32 v169, v169
	v_cvt_pk_bf16_f32 v74, v74, v75
	v_cvt_pk_bf16_f32 v75, v76, v77
	v_cvt_pk_bf16_f32 v76, v78, v79
	v_cvt_pk_bf16_f32 v77, v80, v81
	v_cvt_pk_bf16_f32 v78, v160, v161
	v_cvt_pk_bf16_f32 v79, v164, v165
	v_cvt_pk_bf16_f32 v80, v166, v167
	v_cvt_pk_bf16_f32 v81, v168, v169
	s_waitcnt lgkmcnt(0)
	v_fmamk_f32 v160, v90, 0x3fb8aa3b, v205
	v_fmamk_f32 v161, v91, 0x3fb8aa3b, v205
	v_fmamk_f32 v164, v92, 0x3fb8aa3b, v205
	v_mfma_f32_16x16x32_bf16 v[46:49], v[220:223], v[74:77], v[46:49]
	v_fmamk_f32 v165, v93, 0x3fb8aa3b, v205
	s_mov_b32 s10, s8
	s_mov_b32 s11, s8
	s_mov_b32 s9, s8
	v_mfma_f32_16x16x32_bf16 v[42:45], v[228:231], v[74:77], v[42:45]
	v_mov_b64_e32 v[92:93], s[10:11]
	v_mov_b64_e32 v[90:91], s[8:9]
	v_fmamk_f32 v166, v94, 0x3fb8aa3b, v205
	v_fmamk_f32 v167, v95, 0x3fb8aa3b, v205
	v_mfma_f32_16x16x32_bf16 v[38:41], v[236:239], v[74:77], v[38:41]
	v_fmamk_f32 v168, v96, 0x3fb8aa3b, v205
	v_fmamk_f32 v169, v97, 0x3fb8aa3b, v205
	v_fmamk_f32 v170, v82, 0x3fb8aa3b, v205
	v_fmamk_f32 v171, v83, 0x3fb8aa3b, v205
	v_mfma_f32_16x16x32_bf16 v[34:37], v[244:247], v[74:77], v[34:37]
	v_fmamk_f32 v172, v84, 0x3fb8aa3b, v205
	v_fmamk_f32 v173, v85, 0x3fb8aa3b, v205
	v_fmamk_f32 v174, v86, 0x3fb8aa3b, v205
	v_fmamk_f32 v175, v87, 0x3fb8aa3b, v205
	v_mfma_f32_16x16x32_bf16 v[46:49], v[224:227], v[78:81], v[46:49]
	v_fmamk_f32 v176, v88, 0x3fb8aa3b, v205
	v_fmamk_f32 v177, v89, 0x3fb8aa3b, v205
	v_exp_f32_e32 v160, v160
	v_exp_f32_e32 v161, v161
	v_mfma_f32_16x16x32_bf16 v[42:45], v[232:235], v[78:81], v[42:45]
	v_exp_f32_e32 v164, v164
	v_exp_f32_e32 v165, v165
	v_exp_f32_e32 v166, v166
	v_exp_f32_e32 v167, v167
	v_mfma_f32_16x16x32_bf16 v[38:41], v[240:243], v[78:81], v[38:41]
	v_exp_f32_e32 v168, v168
	v_exp_f32_e32 v169, v169
	v_exp_f32_e32 v170, v170
	v_exp_f32_e32 v171, v171
	v_mfma_f32_16x16x32_bf16 v[34:37], v[198:201], v[78:81], v[34:37]
	v_exp_f32_e32 v172, v172
	v_exp_f32_e32 v173, v173
	v_exp_f32_e32 v174, v174
	v_exp_f32_e32 v175, v175
	v_mfma_f32_16x16x32_bf16 v[54:57], v[90:93], v[74:77], v[54:57]
	v_exp_f32_e32 v176, v176
	v_exp_f32_e32 v177, v177
	v_cvt_pk_bf16_f32 v82, v160, v161
	v_cvt_pk_bf16_f32 v83, v164, v165
	v_mfma_f32_16x16x32_bf16 v[54:57], v[90:93], v[78:81], v[54:57]
	v_cvt_pk_bf16_f32 v84, v166, v167
	v_cvt_pk_bf16_f32 v85, v168, v169
	v_cvt_pk_bf16_f32 v86, v170, v171
	v_cvt_pk_bf16_f32 v87, v172, v173
	v_cvt_pk_bf16_f32 v88, v174, v175
	v_cvt_pk_bf16_f32 v89, v176, v177
	s_nop 1
	v_mfma_f32_16x16x32_bf16 v[30:33], v[220:223], v[82:85], v[30:33]
	v_mfma_f32_16x16x32_bf16 v[26:29], v[228:231], v[82:85], v[26:29]
	v_mfma_f32_16x16x32_bf16 v[22:25], v[236:239], v[82:85], v[22:25]
	v_mfma_f32_16x16x32_bf16 v[18:21], v[244:247], v[82:85], v[18:21]
	v_mfma_f32_16x16x32_bf16 v[30:33], v[224:227], v[86:89], v[30:33]
	v_mfma_f32_16x16x32_bf16 v[26:29], v[232:235], v[86:89], v[26:29]
	v_mfma_f32_16x16x32_bf16 v[22:25], v[240:243], v[86:89], v[22:25]
	v_mfma_f32_16x16x32_bf16 v[18:21], v[198:201], v[86:89], v[18:21]
	v_mfma_f32_16x16x32_bf16 v[50:53], v[90:93], v[82:85], v[50:53]
	v_mfma_f32_16x16x32_bf16 v[50:53], v[90:93], v[86:89], v[50:53]
	s_add_i32 s28, s28, 64
	s_add_i32 s71, s71, 1
	v_subrev_u32_e32 v178, 64, v178
	s_xor_b32 s89, s89, 0xc000
	s_cmp_ge_u32 s72, s25
	v_xor_b32_e32 v188, 0xc000, v188
	v_xor_b32_e32 v189, 0xc000, v189
	v_xor_b32_e32 v190, 0xc000, v190
	v_xor_b32_e32 v191, 0xc000, v191
	v_xor_b32_e32 v207, 0xc000, v207
	v_xor_b32_e32 v208, 0xc000, v208
	v_xor_b32_e32 v209, 0xc000, v209
	v_xor_b32_e32 v210, 0xc000, v210
	v_xor_b32_e32 v211, 0xc000, v211
	v_xor_b32_e32 v212, 0xc000, v212
	v_xor_b32_e32 v213, 0xc000, v213
	v_xor_b32_e32 v214, 0xc000, v214
	s_cbranch_scc1 .LBB0_687
	s_branch .LBB0_681
; DI f32x4 mfma16(bf16x8 a, bf16x8 b, f32x4 c) { return __builtin_amdgcn_mfma_f32_16x16x32_bf16(a, b, c, 0, 0, 0); }
; template <int MODE, bool FX>
; DI void attn_compute(const int lane, const bf16_t* Ks, const bf16_t* Vs, const bf16x8 (&qf)[2][2], AttnSt& st, const float (&invl)[2],
;                      int lo, int hi, float (&impA)[4], float (&impE)[4], const float CL) {
;     ...
;   if (MODE != 0) {
; #pragma unroll
;     for (int dt = 0; dt < 4; ++dt) {
;       const int row = dt * 16 + col;
;       const int sw = (row >> 1) & 7;
; #pragma unroll
;       for (int c = 0; c < 2; ++c) {
;         uint2 a = *(const uint2*)(Vs + row * 64 + (((4 * c + (quad >> 1)) ^ sw) << 3) + (quad & 1) * 4);
;         uint2 b = *(const uint2*)(Vs + row * 64 + (((4 * c + 2 + (quad >> 1)) ^ sw) << 3) + (quad & 1) * 4);
;         bf16x8 vf = mk8(a.x, a.y, b.x, b.y);
; #pragma unroll
;         for (int hh = 0; hh < 2; ++hh) st.O[hh][dt] = mfma16(vf, pf[hh][c], st.O[hh][dt]);
;       }
;     }
;     if (FX && MODE == 2) {
;       const bf16x8 ones = mk8(0x3F803F80u, 0x3F803F80u, 0x3F803F80u, 0x3F803F80u);
; #pragma unroll
;       for (int c = 0; c < 2; ++c)
; #pragma unroll
;         for (int hh = 0; hh < 2; ++hh) st.L[hh] = mfma16(ones, pf[hh][c], st.L[hh]);
;     }
; template <bool FX>
; DI void nsa_tile(const Params& p, int b, int g, int tile, bf16_t* lds, const float CL) {
;     ...
;       for (int s = s0; s <= cur; ++s) {
;         __syncthreads();
;         tile64_sstore(tid, Ks, rk0, rk1);
;         tile64_sstore(tid, Vs, rv0, rv1);
;         __syncthreads();
;         if (s < cur) {
;           tile64_gload(tid, rk0, rk1, kb + (size_t)(s + 1) * 64 * ZS, ZS);
;           tile64_gload(tid, rv0, rv1, vwT + (s + 1) * 64, TS);
;         }
.LBB0_680:
	ds_read2st64_b64 v[90:93], v207 offset0:16 offset1:20
	ds_read2st64_b64 v[94:97], v208 offset0:16 offset1:20
	v_cvt_pk_bf16_f32 v82, v160, v161
	v_cvt_pk_bf16_f32 v83, v164, v165
	v_cvt_pk_bf16_f32 v84, v166, v167
	s_waitcnt lgkmcnt(1)
	v_mov_b32_e32 v98, v90
	v_mov_b32_e32 v99, v91
	s_waitcnt lgkmcnt(0)
	v_mov_b32_e32 v100, v94
	v_mov_b32_e32 v101, v95
	v_cvt_pk_bf16_f32 v85, v168, v169
	v_mov_b32_e32 v94, v92
	v_mfma_f32_16x16x32_bf16 v[46:49], v[98:101], v[74:77], v[46:49]
	v_mov_b32_e32 v95, v93
	v_cvt_pk_bf16_f32 v86, v170, v171
	v_cvt_pk_bf16_f32 v87, v172, v173
	v_mfma_f32_16x16x32_bf16 v[30:33], v[98:101], v[82:85], v[30:33]
	ds_read2st64_b64 v[98:101], v209 offset0:16 offset1:20
	ds_read2st64_b64 v[102:105], v210 offset0:16 offset1:20
	ds_read_b64 v[90:91], v207 offset:12288
	ds_read_b64 v[92:93], v208 offset:12288
	v_cvt_pk_bf16_f32 v88, v174, v175
	s_waitcnt lgkmcnt(0)
	v_mfma_f32_16x16x32_bf16 v[38:41], v[90:93], v[74:77], v[38:41]
	v_cvt_pk_bf16_f32 v89, v176, v177
	s_mov_b32 s10, s8
	s_mov_b32 s11, s8
	v_mfma_f32_16x16x32_bf16 v[22:25], v[90:93], v[82:85], v[22:25]
	ds_read_b64 v[90:91], v209 offset:12288
	ds_read_b64 v[92:93], v210 offset:12288
	s_mov_b32 s9, s8
	v_mov_b32_e32 v106, v98
	s_waitcnt lgkmcnt(0)
	v_mfma_f32_16x16x32_bf16 v[38:41], v[90:93], v[78:81], v[38:41]
	v_mov_b32_e32 v107, v99
	v_mov_b32_e32 v108, v102
	v_mov_b32_e32 v109, v103
	v_mfma_f32_16x16x32_bf16 v[22:25], v[90:93], v[86:89], v[22:25]
	ds_read_b64 v[90:91], v211 offset:8192
	ds_read_b64 v[92:93], v212 offset:8192
	v_mov_b32_e32 v102, v100
	v_mov_b32_e32 v103, v101
	s_waitcnt lgkmcnt(0)
	v_mfma_f32_16x16x32_bf16 v[34:37], v[90:93], v[74:77], v[34:37]
	s_add_i32 s28, s28, 64
	s_add_i32 s71, s71, 1
	v_subrev_u32_e32 v178, 64, v178
	v_mfma_f32_16x16x32_bf16 v[18:21], v[90:93], v[82:85], v[18:21]
	ds_read_b64 v[90:91], v213 offset:8192
	ds_read_b64 v[92:93], v214 offset:8192
	s_xor_b32 s89, s89, 0xc000
	s_cmp_ge_u32 s72, s25
	s_waitcnt lgkmcnt(0)
	v_mfma_f32_16x16x32_bf16 v[34:37], v[90:93], v[78:81], v[34:37]
	v_mfma_f32_16x16x32_bf16 v[18:21], v[90:93], v[86:89], v[18:21]
	v_mov_b64_e32 v[92:93], s[10:11]
	v_mov_b64_e32 v[90:91], s[8:9]
	v_mfma_f32_16x16x32_bf16 v[42:45], v[94:97], v[74:77], v[42:45]
	v_mfma_f32_16x16x32_bf16 v[26:29], v[94:97], v[82:85], v[26:29]
	v_mfma_f32_16x16x32_bf16 v[54:57], v[90:93], v[74:77], v[54:57]
	v_mfma_f32_16x16x32_bf16 v[50:53], v[90:93], v[82:85], v[50:53]
	v_mfma_f32_16x16x32_bf16 v[46:49], v[106:109], v[78:81], v[46:49]
	v_mfma_f32_16x16x32_bf16 v[30:33], v[106:109], v[86:89], v[30:33]
	v_mfma_f32_16x16x32_bf16 v[42:45], v[102:105], v[78:81], v[42:45]
	v_mfma_f32_16x16x32_bf16 v[26:29], v[102:105], v[86:89], v[26:29]
	v_mfma_f32_16x16x32_bf16 v[54:57], v[90:93], v[78:81], v[54:57]
	v_mfma_f32_16x16x32_bf16 v[50:53], v[90:93], v[86:89], v[50:53]
	v_xor_b32_e32 v188, 0xc000, v188
	v_xor_b32_e32 v189, 0xc000, v189
	v_xor_b32_e32 v190, 0xc000, v190
	v_xor_b32_e32 v191, 0xc000, v191
	v_xor_b32_e32 v207, 0xc000, v207
	v_xor_b32_e32 v208, 0xc000, v208
	v_xor_b32_e32 v209, 0xc000, v209
	v_xor_b32_e32 v210, 0xc000, v210
	v_xor_b32_e32 v211, 0xc000, v211
	v_xor_b32_e32 v212, 0xc000, v212
	v_xor_b32_e32 v213, 0xc000, v213
	v_xor_b32_e32 v214, 0xc000, v214
	s_cbranch_scc1 .LBB0_687
.LBB0_681:
	s_add_i32 s72, s71, -1
	s_mul_i32 s2, s71, 0xa8c00
	s_mul_hi_u32 s3, s71, 0xa8c00
	s_add_u32 s2, s30, s2
	s_addc_u32 s3, s31, s3
	v_lshl_add_u64 v[58:59], v[130:131], 1, s[2:3]
	v_lshl_add_u64 v[60:61], v[134:135], 1, s[2:3]
	s_lshl_b64 s[2:3], s[28:29], 1
	s_add_u32 s2, s0, s2
	s_addc_u32 s3, s1, s3
	v_lshl_add_u64 v[66:67], v[138:139], 1, s[2:3]
	v_lshl_add_u64 v[68:69], v[142:143], 1, s[2:3]
	s_movk_i32 s84, 0x800
	v_lshl_add_u64 v[58:59], v[58:59], 0, v[202:203]
	v_lshl_add_u64 v[62:63], v[60:61], 0, v[202:203]
	v_lshl_add_u64 v[66:67], v[66:67], 0, v[202:203]
	v_lshl_add_u64 v[70:71], v[68:69], 0, v[202:203]
	v_lshl_add_u64 v[58:59], v[58:59], 0, s[84:85]
	v_lshl_add_u64 v[62:63], v[62:63], 0, s[84:85]
	s_cmp_ge_u32 s72, s25
	s_waitcnt vmcnt(0)
	s_barrier
	s_cbranch_scc1 .LBB0_683
	s_mov_b32 m0, s88
	s_nop 0
	global_load_lds_dwordx4 v[58:59], off
	s_add_u32 m0, s88, 0x1000
	s_nop 0
	global_load_lds_dwordx4 v[62:63], off
	s_add_u32 m0, s88, 0x2000
	s_nop 0
	global_load_lds_dwordx4 v[66:67], off
	s_add_u32 m0, s88, 0x3000
	s_nop 0
	global_load_lds_dwordx4 v[70:71], off
	s_xor_b32 s88, s88, 0xc000

; DI float bf2f(bf16_t h) { return __uint_as_float(((unsigned)h) << 16); }
; DI float sigmoidf(float x) { return __builtin_amdgcn_rcpf(1.f + __expf(-x)); }
; template <bool FX>
; DI void nsa_tile(const Params& p, int b, int g, int tile, bf16_t* lds, const float CL) {
;     ...
;     {
;       float sc[2];
; #pragma unroll
;       for (int h = 0; h < 2; ++h) {
;         float l;
;         if (FX) {
;           l = st.L[h][0];
;         } else {
;           l = st.l[h];
;           l += shx(l, 16, lane);
;           l += shx(l, 32, lane);
;         }
;         sc[h] = (l > 0.f) ? sigmoidf(bf2f(ztok[C_GT + 2 * 8 + g * 4 + hp * 2 + h])) / l : 0.f;
;       }
.LBB0_687:
	v_xor_b32_e32 v188, s89, v188
	v_xor_b32_e32 v189, s89, v189
	v_xor_b32_e32 v190, s89, v190
	v_xor_b32_e32 v191, s89, v191
	v_xor_b32_e32 v207, s89, v207
	v_xor_b32_e32 v208, s89, v208
	v_xor_b32_e32 v209, s89, v209
	v_xor_b32_e32 v210, s89, v210
	v_xor_b32_e32 v211, s89, v211
	v_xor_b32_e32 v212, s89, v212
	v_xor_b32_e32 v213, s89, v213
	v_xor_b32_e32 v214, s89, v214
	v_mov_b32_e32 v2, 0
	s_nop 4
	v_cmp_lt_f32_e32 vcc, 0, v54
	v_mov_b32_e32 v4, 0
	v_mov_b32_e32 v5, 0
	v_mov_b32_e32 v6, 0
	v_mov_b32_e32 v7, 0
	s_and_saveexec_b64 s[2:3], vcc
	s_cbranch_execz .LBB0_689
	s_lshl_b32 s28, s70, 1
	v_lshl_add_u64 v[4:5], v[114:115], 0, s[28:29]
	global_load_ushort v3, v[4:5], off offset:2592
	s_waitcnt vmcnt(0)
	v_lshlrev_b32_e32 v3, 16, v3
	v_mul_f32_e32 v3, 0xbfb8aa3b, v3
	v_exp_f32_e32 v3, v3
	s_nop 0
	v_add_f32_e32 v3, 1.0, v3
	v_rcp_f32_e32 v3, v3
	s_nop 0
	v_div_scale_f32 v4, s[4:5], v54, v54, v3
	v_rcp_f32_e32 v5, v4
	v_div_scale_f32 v6, vcc, v3, v54, v3
	v_fma_f32 v7, -v4, v5, 1.0
	v_fmac_f32_e32 v5, v7, v5
	v_mul_f32_e32 v7, v6, v5
	v_fma_f32 v8, -v4, v7, v6
	v_fmac_f32_e32 v7, v8, v5
	v_fma_f32 v4, -v4, v7, v6
	v_div_fmas_f32 v4, v4, v5, v7
	v_div_fixup_f32 v4, v4, v54, v3
	v_mov_b32_e32 v5, v4
	v_mov_b32_e32 v6, v4
	v_mov_b32_e32 v7, v4
